# combo10 = combo6 + the grid barrier between the RWKV output phase and the mLSTM chunk-prep phase dropped (the two phases touch disjoint data)
# speedup vs baseline: 1.0037x; 1.0015x over previous
.LBB0_1285:
	v_readlane_b32 s20, v252, 7
	v_readlane_b32 s2, v254, 44
	v_readlane_b32 s21, v252, 8
	s_or_b32 s24, s2, 9
	s_mov_b64 s[4:5], s[20:21]
	s_cmp_le_i32 s4, s24
	s_cselect_b64 s[2:3], -1, 0
	s_cmp_lt_i32 s24, s5
	v_readlane_b32 s12, v252, 12
	s_cselect_b64 s[4:5], -1, 0
	v_readlane_b32 s13, v252, 13
	s_and_b64 s[4:5], s[12:13], s[4:5]
	s_and_b64 s[2:3], s[2:3], s[4:5]
	s_andn2_b64 vcc, exec, s[2:3]
	v_readlane_b32 s22, v252, 9
	v_readlane_b32 s23, v252, 10
	s_cbranch_vccnz .LBB0_1335
	v_mbcnt_lo_u32_b32 v0, -1, 0
	v_mbcnt_hi_u32_b32 v0, -1, v0
	s_waitcnt vmcnt(0)
	s_waitcnt vmcnt(0)
	v_sub_u32_e32 v0, 0, v0
	s_mov_b64 vcc, 0
	s_barrier
	s_and_saveexec_b64 s[2:3], vcc
	s_cbranch_execz .LBB0_1334
	v_readlane_b32 s4, v252, 11
	s_waitcnt vmcnt(0) expcnt(0) lgkmcnt(0)
	s_nop 0
	v_mov_b32_e32 v0, s4
	ds_read_b32 v2, v0
	ds_read_b32 v0, v0 offset:4
	s_waitcnt lgkmcnt(1)
	v_cmp_ne_u32_e32 vcc, 0, v2
	s_cbranch_vccnz .LBB0_1302
	v_readlane_b32 s12, v252, 0
	v_readlane_b32 s13, v252, 1
	s_load_dwordx2 s[4:5], s[12:13], 0x4
	v_readlane_b32 s12, v252, 2
	s_mov_b32 s23, 1
	s_waitcnt lgkmcnt(0)
	s_mul_i32 s22, s4, s12
	s_mul_i32 s22, s22, s5
	s_branch .LBB0_1290
